# v10 + attention softmax: DPP row shuffles replace ds_bpermute xor-shuffles, bias LDS reads hoisted branch-free
# speedup vs baseline: 1.0163x; 1.0033x over previous
; __device__ void attn_items(const Params& p, unsigned char* shm) {
;     ...
;         f32x4 s[9];
; #pragma unroll
;         for (int kt = 0; kt < 9; ++kt) { const bf16_t* kr = Ks + (16 * w + 16 * kt + fr) * 72 + fq * 8;
;             f32x4 a = (f32x4){0.f, 0.f, 0.f, 0.f};
;             a = __builtin_amdgcn_mfma_f32_16x16x32_bf16(aq0, *(const bf16x8*)kr, a, 0, 0, 0);
;             a = __builtin_amdgcn_mfma_f32_16x16x32_bf16(aq1, *(const bf16x8*)(kr + 32), a, 0, 0, 0); s[kt] = a; }
;         float mx[4], ls[4];
; #pragma unroll
;         for (int i = 0; i < 4; ++i) { const int qi = fq * 4 + i; float m = -3.0e38f;
; #pragma unroll
;             for (int kt = 0; kt < 9; ++kt) { const int rel = 16 * kt + fr - 64 - qi, klat = G.q0 - 64 + 16 * w + 16 * kt + fr;
;                 const bool ok = rel >= -64 && rel <= 64 && klat >= 0 && klat < G.n_lat; const int bi = min(max(rel + 64, 0), 128);
;                 const float v = ok ? s[kt][i] + bs[bi] : -1.0e30f; s[kt][i] = v; m = fmaxf(m, v); }
.LBB0_373:
	v_add_u32_e32 v0, v101, v114
	ds_read_b128 v[60:63], v0
	ds_read_b128 v[64:67], v0 offset:64
	s_mul_hi_i32 s0, s4, 0x2aaaaaab
	s_lshr_b32 s1, s0, 31
	s_waitcnt lgkmcnt(1)
	v_mfma_f32_16x16x32_bf16 v[60:63], v[56:59], v[60:63], 0
	s_ashr_i32 s0, s0, 5
	s_add_i32 s58, s0, s1
	ds_read_b128 v[68:71], v164 offset:64
	s_waitcnt lgkmcnt(1)
	v_mfma_f32_16x16x32_bf16 v[60:63], v[52:55], v[64:67], v[60:63]
	ds_read_b128 v[64:67], v164
	s_mul_i32 s0, s58, 0xffffff40
	s_add_i32 s0, s4, s0
	s_waitcnt lgkmcnt(0)
	v_mfma_f32_16x16x32_bf16 v[64:67], v[56:59], v[64:67], 0
	s_and_b32 s4, s0, 15
	ds_read_b128 v[72:75], v165 offset:64
	s_sub_i32 s5, s0, 64
	v_mfma_f32_16x16x32_bf16 v[64:67], v[52:55], v[68:71], v[64:67]
	ds_read_b128 v[68:71], v165
	s_cmp_lt_i32 s0, 64
	s_cselect_b64 s[60:61], -1, 0
	s_waitcnt lgkmcnt(0)
	v_mfma_f32_16x16x32_bf16 v[68:71], v[56:59], v[68:71], 0
	ds_read_b128 v[76:79], v166 offset:64
	s_and_b64 s[0:1], s[60:61], exec
	s_movk_i32 s0, 0x800
	v_mfma_f32_16x16x32_bf16 v[68:71], v[52:55], v[72:75], v[68:71]
	ds_read_b128 v[72:75], v166
	s_cselect_b32 s6, s4, s5
	s_cselect_b32 s0, s0, 0x4000
	s_waitcnt lgkmcnt(0)
	v_mfma_f32_16x16x32_bf16 v[72:75], v[56:59], v[72:75], 0
	ds_read_b128 v[80:83], v167 offset:64
	s_and_b32 s1, s58, -8
	s_cmp_eq_u32 s1, 8
	v_mfma_f32_16x16x32_bf16 v[72:75], v[52:55], v[76:79], v[72:75]
	ds_read_b128 v[76:79], v167
	s_cselect_b32 s1, 2, 4
	s_cmp_gt_u32 s58, 7
	s_waitcnt lgkmcnt(0)
	v_mfma_f32_16x16x32_bf16 v[76:79], v[56:59], v[76:79], 0
	ds_read_b128 v[84:87], v168 offset:64
	s_cselect_b32 s4, s1, 0
	s_lshr_b32 s8, s0, s4
	v_mfma_f32_16x16x32_bf16 v[76:79], v[52:55], v[80:83], v[76:79]
	ds_read_b128 v[80:83], v168
	s_lshr_b32 s0, s8, 7
	s_add_i32 s0, s0, -1
	s_waitcnt lgkmcnt(0)
	v_mfma_f32_16x16x32_bf16 v[80:83], v[56:59], v[80:83], 0
	ds_read_b128 v[88:91], v169 offset:64
	s_and_b32 s0, s0, s6
	s_lshl_b32 s5, s0, 7
	v_mfma_f32_16x16x32_bf16 v[80:83], v[52:55], v[84:87], v[80:83]
	ds_read_b128 v[84:87], v169
	s_mul_i32 s0, s58, 0x210
	ds_read_b128 v[176:179], v170 offset:64
	s_waitcnt lgkmcnt(1)
	v_mfma_f32_16x16x32_bf16 v[84:87], v[56:59], v[84:87], 0
	s_add_i32 s7, s0, 0
	v_add_u32_e32 v2, s5, v102
	v_readlane_b32 s0, v254, 49
	v_mfma_f32_16x16x32_bf16 v[84:87], v[52:55], v[88:91], v[84:87]
	ds_read_b128 v[88:91], v170
	v_or_b32_e32 v0, v2, v93
	v_cmp_lt_i32_e32 vcc, -1, v2
	s_waitcnt lgkmcnt(0)
	v_mfma_f32_16x16x32_bf16 v[88:91], v[56:59], v[88:91], 0
	v_readlane_b32 s1, v254, 50
	s_add_i32 s7, s7, 0x1d800
	s_and_b64 s[0:1], s[0:1], vcc
	v_mfma_f32_16x16x32_bf16 v[88:91], v[52:55], v[176:179], v[88:91]
	ds_read_b128 v[176:179], v171
	v_cmp_gt_i32_e64 s[74:75], s8, v0
	s_and_b64 s[18:19], s[0:1], s[74:75]
	s_waitcnt lgkmcnt(0)
	v_mfma_f32_16x16x32_bf16 v[56:59], v[56:59], v[176:179], 0
	ds_read_b128 v[176:179], v171 offset:64
	v_mov_b32_e32 v3, 0xf149f2ca
	s_waitcnt lgkmcnt(0)
	v_mfma_f32_16x16x32_bf16 v[52:55], v[52:55], v[176:179], v[56:59]
	s_nop 3
	v_lshl_add_u32 v57, v115, 2, s7
	ds_read_b32 v184, v57
	ds_read_b32 v185, v57 offset:64
	ds_read_b32 v186, v57 offset:128
	ds_read_b32 v187, v57 offset:192
	ds_read_b32 v188, v57 offset:256
	ds_read_b32 v189, v57 offset:320
	ds_read_b32 v190, v57 offset:384
	ds_read_b32 v191, v57 offset:448
	ds_read_b32 v192, v57 offset:512
	v_lshl_add_u32 v232, v116, 2, s7
	ds_read_b32 v193, v232
	ds_read_b32 v194, v232 offset:64
	ds_read_b32 v196, v232 offset:128
	ds_read_b32 v197, v232 offset:192
	ds_read_b32 v198, v232 offset:256
	ds_read_b32 v199, v232 offset:320
	ds_read_b32 v200, v232 offset:384
	ds_read_b32 v201, v232 offset:448
	ds_read_b32 v202, v232 offset:512
	v_lshl_add_u32 v233, v118, 2, s7
	ds_read_b32 v203, v233
	ds_read_b32 v204, v233 offset:64
	ds_read_b32 v205, v233 offset:128
	ds_read_b32 v206, v233 offset:192
	ds_read_b32 v207, v233 offset:256
	ds_read_b32 v208, v233 offset:320
	ds_read_b32 v209, v233 offset:384
	ds_read_b32 v210, v233 offset:448
	ds_read_b32 v211, v233 offset:512
	v_lshl_add_u32 v232, v120, 2, s7
	ds_read_b32 v212, v232
	ds_read_b32 v213, v232 offset:64
	ds_read_b32 v214, v232 offset:128
	ds_read_b32 v215, v232 offset:192
	ds_read_b32 v216, v232 offset:256
	ds_read_b32 v217, v232 offset:320
	ds_read_b32 v218, v232 offset:384
	ds_read_b32 v219, v232 offset:448
	ds_read_b32 v220, v232 offset:512
	v_mov_b32_e32 v56, 0xf149f2ca
	s_waitcnt lgkmcnt(0)
; __device__ void attn_items(const Params& p, unsigned char* shm) {
;     ...
;         for (int i = 0; i < 4; ++i) { const int qi = fq * 4 + i; float m = -3.0e38f;
; #pragma unroll
;             for (int kt = 0; kt < 9; ++kt) { const int rel = 16 * kt + fr - 64 - qi, klat = G.q0 - 64 + 16 * w + 16 * kt + fr;
;                 const bool ok = rel >= -64 && rel <= 64 && klat >= 0 && klat < G.n_lat; const int bi = min(max(rel + 64, 0), 128);
;                 const float v = ok ? s[kt][i] + bs[bi] : -1.0e30f; s[kt][i] = v; m = fmaxf(m, v); }
;             m = fmaxf(m, __shfl_xor(m, 1)); m = fmaxf(m, __shfl_xor(m, 2)); m = fmaxf(m, __shfl_xor(m, 4)); m = fmaxf(m, __shfl_xor(m, 8));
;             float sum = 0.f;
; #pragma unroll
;             for (int kt = 0; kt < 9; ++kt) { const float pv = __expf(s[kt][i] - m); s[kt][i] = pv; sum += pv; }
;             sum += __shfl_xor(sum, 1); sum += __shfl_xor(sum, 2); sum += __shfl_xor(sum, 4); sum += __shfl_xor(sum, 8);
;             mx[i] = m; ls[i] = sum; }
	v_add_f32_e32 v184, v60, v184
	v_cndmask_b32_e64 v56, v56, v184, s[18:19]
	v_add_u32_e32 v0, v2, v127
	s_movk_i32 s0, 0xffef
	v_cmp_lt_i32_e64 s[76:77], s0, v2
	v_cmp_gt_i32_e64 s[78:79], s8, v0
	s_and_b64 s[62:63], s[76:77], s[78:79]
	v_add_f32_e32 v185, v64, v185
	v_cndmask_b32_e64 v3, v3, v185, s[62:63]
	v_add_u32_e32 v0, v2, v129
	s_movk_i32 s0, 0xffdf
	v_cmp_lt_i32_e64 s[76:77], s0, v2
	v_cmp_gt_i32_e64 s[78:79], s8, v0
	s_and_b64 s[64:65], s[76:77], s[78:79]
	v_mov_b32_e32 v58, 0xf149f2ca
	v_mov_b32_e32 v59, 0xf149f2ca
	v_add_f32_e32 v186, v68, v186
	v_cndmask_b32_e64 v59, v59, v186, s[64:65]
	v_add_u32_e32 v0, v2, v132
	s_movk_i32 s0, 0xffcf
	v_cmp_lt_i32_e64 s[76:77], s0, v2
	v_cmp_gt_i32_e64 s[78:79], s8, v0
	s_and_b64 s[66:67], s[76:77], s[78:79]
	v_add_f32_e32 v187, v72, v187
	v_cndmask_b32_e64 v58, v58, v187, s[66:67]
	v_add_u32_e32 v0, s5, v99
	v_or_b32_e32 v60, v0, v93
	v_cmp_lt_i32_e64 s[76:77], -1, v0
	v_cmp_gt_i32_e64 s[78:79], s8, v60
	s_and_b64 s[68:69], s[76:77], s[78:79]
	v_mov_b32_e32 v60, 0xf149f2ca
	v_mov_b32_e32 v64, 0xf149f2ca
	v_add_f32_e32 v188, v76, v188
	v_cndmask_b32_e64 v64, v64, v188, s[68:69]
	v_add_u32_e32 v68, v2, v150
	s_movk_i32 s0, 0xffaf
	v_cmp_lt_i32_e64 s[76:77], s0, v2
	v_cmp_gt_i32_e64 s[78:79], s8, v68
	s_and_b64 s[70:71], s[76:77], s[78:79]
	v_add_f32_e32 v189, v80, v189
	v_cndmask_b32_e64 v60, v60, v189, s[70:71]
	v_add_u32_e32 v68, v2, v151
	s_movk_i32 s0, 0xff9f
	v_cmp_lt_i32_e64 s[76:77], s0, v2
	v_cmp_gt_i32_e64 s[78:79], s8, v68
	s_and_b64 s[72:73], s[76:77], s[78:79]
	v_mov_b32_e32 v72, 0xf149f2ca
	v_mov_b32_e32 v76, 0xf149f2ca
	v_add_f32_e32 v190, v84, v190
	v_cndmask_b32_e64 v76, v76, v190, s[72:73]
	v_add_u32_e32 v68, v2, v152
	s_movk_i32 s0, 0xff8f
	v_cmp_lt_i32_e64 s[76:77], s0, v2
	v_cmp_gt_i32_e64 s[78:79], s8, v68
	s_and_b64 s[38:39], s[76:77], s[78:79]
	v_add_f32_e32 v191, v88, v191
	v_cndmask_b32_e64 v72, v72, v191, s[38:39]
	v_readlane_b32 s0, v254, 37
	v_add_u32_e32 v68, v2, v153
	v_cmp_lt_i32_e64 s[76:77], s23, v2
	v_readlane_b32 s1, v254, 38
	s_and_b64 s[0:1], s[0:1], s[76:77]
	v_cmp_gt_i32_e64 s[78:79], s8, v68
	s_and_b64 s[8:9], s[0:1], s[78:79]
	v_mov_b32_e32 v68, 0xf149f2ca
	v_mov_b32_e32 v84, 0xf149f2ca
	v_add_f32_e32 v192, v52, v192
	v_cndmask_b32_e64 v84, v84, v192, s[8:9]
	v_max_f32_e32 v2, v56, v56
	v_max_f32_e32 v2, 0xff61b1e6, v2
	v_max3_f32 v2, v2, v3, v59
	v_max3_f32 v2, v2, v58, v64
	v_max3_f32 v2, v2, v60, v76
	v_max3_f32 v2, v2, v72, v84
	s_nop 1
	v_mov_b32_dpp v52, v2 quad_perm:[1,0,3,2] row_mask:0xf bank_mask:0xf
	v_readlane_b32 s0, v255, 0
	v_readlane_b32 s1, v255, 1
	s_and_b64 s[0:1], s[0:1], vcc
	s_and_b64 s[8:9], s[0:1], s[74:75]
	s_waitcnt lgkmcnt(0)
	v_max_f32_e32 v52, v52, v52
	v_max_f32_e32 v2, v2, v52
	s_nop 1
	v_mov_b32_dpp v52, v2 quad_perm:[2,3,0,1] row_mask:0xf bank_mask:0xf
	s_waitcnt lgkmcnt(0)
	v_max_f32_e32 v52, v52, v52
	v_max_f32_e32 v2, v2, v52
	s_nop 1
	v_mov_b32_dpp v52, v2 row_shl:4 row_mask:0xf bank_mask:0x5
	v_mov_b32_dpp v52, v2 row_shr:4 row_mask:0xf bank_mask:0xa
	s_waitcnt lgkmcnt(0)
	v_max_f32_e32 v52, v52, v52
	v_max_f32_e32 v2, v2, v52
	s_nop 1
	v_mov_b32_dpp v52, v2 row_shl:8 row_mask:0xf bank_mask:0x3
	v_mov_b32_dpp v52, v2 row_shr:8 row_mask:0xf bank_mask:0xc
	s_waitcnt lgkmcnt(0)
	v_max_f32_e32 v52, v52, v52
	v_max_f32_e32 v2, v2, v52
	v_sub_f32_e32 v52, v56, v2
	v_sub_f32_e32 v3, v3, v2
	v_mul_f32_e32 v52, 0x3fb8aa3b, v52
	v_sub_f32_e32 v56, v59, v2
	v_mul_f32_e32 v3, 0x3fb8aa3b, v3
	v_exp_f32_e32 v80, v52
	v_sub_f32_e32 v57, v58, v2
	v_sub_f32_e32 v59, v60, v2
	v_sub_f32_e32 v60, v76, v2
	v_mul_f32_e32 v56, 0x3fb8aa3b, v56
	v_exp_f32_e32 v76, v3
	v_sub_f32_e32 v58, v64, v2
	v_mul_f32_e32 v57, 0x3fb8aa3b, v57
	v_exp_f32_e32 v64, v56
	v_mul_f32_e32 v58, 0x3fb8aa3b, v58
	v_mul_f32_e32 v88, 0x3fb8aa3b, v60
	v_exp_f32_e32 v60, v57
	v_mul_f32_e32 v59, 0x3fb8aa3b, v59
	v_exp_f32_e32 v57, v58
	v_add_f32_e32 v3, 0, v80
	v_sub_f32_e32 v72, v72, v2
	v_exp_f32_e32 v56, v59
	v_add_f32_e32 v3, v76, v3
	v_exp_f32_e32 v52, v88
	v_add_f32_e32 v3, v64, v3
	v_mul_f32_e32 v58, 0x3fb8aa3b, v72
	v_sub_f32_e32 v59, v84, v2
	v_add_f32_e32 v3, v60, v3
	v_exp_f32_e32 v58, v58
	v_mul_f32_e32 v59, 0x3fb8aa3b, v59
	v_add_f32_e32 v3, v57, v3
	v_exp_f32_e32 v59, v59
	v_add_f32_e32 v3, v56, v3
	v_add_f32_e32 v3, v52, v3
	v_add_f32_e32 v3, v58, v3
	v_add_f32_e32 v3, v59, v3
	s_nop 1
	v_mov_b32_dpp v72, v3 quad_perm:[1,0,3,2] row_mask:0xf bank_mask:0xf
	s_waitcnt lgkmcnt(0)
	v_add_f32_e32 v3, v3, v72
	s_nop 1
	v_mov_b32_dpp v72, v3 quad_perm:[2,3,0,1] row_mask:0xf bank_mask:0xf
	s_waitcnt lgkmcnt(0)
	v_add_f32_e32 v3, v3, v72
	s_nop 1
	v_mov_b32_dpp v72, v3 row_shl:4 row_mask:0xf bank_mask:0x5
	v_mov_b32_dpp v72, v3 row_shr:4 row_mask:0xf bank_mask:0xa
	s_waitcnt lgkmcnt(0)
	v_add_f32_e32 v176, v3, v72
	s_nop 1
	v_mov_b32_dpp v177, v176 row_shl:8 row_mask:0xf bank_mask:0x3
	v_mov_b32_dpp v177, v176 row_shr:8 row_mask:0xf bank_mask:0xc
	v_lshl_add_u32 v3, v116, 2, s7
	v_add_f32_e32 v193, v61, v193
	v_cndmask_b32_e64 v68, v68, v193, s[8:9]
	v_mov_b32_e32 v61, 0xf149f2ca
	v_mov_b32_e32 v72, 0xf149f2ca
	v_add_f32_e32 v194, v65, v194
	v_cndmask_b32_e64 v72, v72, v194, s[62:63]
	v_add_f32_e32 v196, v69, v196
	v_cndmask_b32_e64 v61, v61, v196, s[64:65]
	v_mov_b32_e32 v65, 0xf149f2ca
	v_mov_b32_e32 v69, 0xf149f2ca
	v_add_f32_e32 v197, v73, v197
	v_cndmask_b32_e64 v69, v69, v197, s[66:67]
	v_add_f32_e32 v198, v77, v198
	v_cndmask_b32_e64 v65, v65, v198, s[68:69]
	v_mov_b32_e32 v73, 0xf149f2ca
	v_mov_b32_e32 v84, 0xf149f2ca
	v_add_f32_e32 v199, v81, v199
	v_cndmask_b32_e64 v84, v84, v199, s[70:71]
	v_add_f32_e32 v200, v85, v200
	v_cndmask_b32_e64 v73, v73, v200, s[72:73]
	v_mov_b32_e32 v77, 0xf149f2ca
	v_mov_b32_e32 v81, 0xf149f2ca
	v_add_f32_e32 v201, v89, v201
	v_cndmask_b32_e64 v81, v81, v201, s[38:39]
	v_readlane_b32 s0, v255, 2
	v_readlane_b32 s1, v255, 3
	s_and_b64 s[0:1], s[0:1], s[76:77]
	s_and_b64 s[8:9], s[0:1], s[78:79]
	v_add_f32_e32 v202, v53, v202
	v_cndmask_b32_e64 v77, v77, v202, s[8:9]
	v_max_f32_e32 v3, v68, v68
	v_max_f32_e32 v3, 0xff61b1e6, v3
	v_max3_f32 v3, v3, v72, v61
	v_max3_f32 v3, v3, v69, v65
	v_max3_f32 v3, v3, v84, v73
	v_max3_f32 v3, v3, v81, v77
	s_nop 1
	v_mov_b32_dpp v53, v3 quad_perm:[1,0,3,2] row_mask:0xf bank_mask:0xf
	v_readlane_b32 s0, v255, 4
	v_readlane_b32 s1, v255, 5
	s_and_b64 s[0:1], s[0:1], vcc
	s_and_b64 s[8:9], s[0:1], s[74:75]
	s_waitcnt lgkmcnt(0)
; __device__ void attn_items(const Params& p, unsigned char* shm) {
;     ...
;         for (int i = 0; i < 4; ++i) { const int qi = fq * 4 + i; float m = -3.0e38f;
; #pragma unroll
;             for (int kt = 0; kt < 9; ++kt) { const int rel = 16 * kt + fr - 64 - qi, klat = G.q0 - 64 + 16 * w + 16 * kt + fr;
;                 const bool ok = rel >= -64 && rel <= 64 && klat >= 0 && klat < G.n_lat; const int bi = min(max(rel + 64, 0), 128);
;                 const float v = ok ? s[kt][i] + bs[bi] : -1.0e30f; s[kt][i] = v; m = fmaxf(m, v); }
;             m = fmaxf(m, __shfl_xor(m, 1)); m = fmaxf(m, __shfl_xor(m, 2)); m = fmaxf(m, __shfl_xor(m, 4)); m = fmaxf(m, __shfl_xor(m, 8));
;             float sum = 0.f;
; #pragma unroll
;             for (int kt = 0; kt < 9; ++kt) { const float pv = __expf(s[kt][i] - m); s[kt][i] = pv; sum += pv; }
;             sum += __shfl_xor(sum, 1); sum += __shfl_xor(sum, 2); sum += __shfl_xor(sum, 4); sum += __shfl_xor(sum, 8);
;             mx[i] = m; ls[i] = sum; }
	v_max_f32_e32 v53, v53, v53
	v_max_f32_e32 v3, v3, v53
	s_nop 1
	v_mov_b32_dpp v53, v3 quad_perm:[2,3,0,1] row_mask:0xf bank_mask:0xf
	s_waitcnt lgkmcnt(0)
	v_max_f32_e32 v53, v53, v53
	v_max_f32_e32 v3, v3, v53
	s_nop 1
	v_mov_b32_dpp v53, v3 row_shl:4 row_mask:0xf bank_mask:0x5
	v_mov_b32_dpp v53, v3 row_shr:4 row_mask:0xf bank_mask:0xa
	s_waitcnt lgkmcnt(0)
	v_max_f32_e32 v53, v53, v53
	v_max_f32_e32 v3, v3, v53
	s_nop 1
	v_mov_b32_dpp v53, v3 row_shl:8 row_mask:0xf bank_mask:0x3
	v_mov_b32_dpp v53, v3 row_shr:8 row_mask:0xf bank_mask:0xc
	s_waitcnt lgkmcnt(0)
	v_max_f32_e32 v53, v53, v53
	v_max_f32_e32 v3, v3, v53
	v_sub_f32_e32 v53, v68, v3
	v_sub_f32_e32 v68, v72, v3
	v_mul_f32_e32 v53, 0x3fb8aa3b, v53
	v_sub_f32_e32 v61, v61, v3
	v_mul_f32_e32 v68, 0x3fb8aa3b, v68
	v_exp_f32_e32 v97, v53
	v_sub_f32_e32 v69, v69, v3
	v_mul_f32_e32 v61, 0x3fb8aa3b, v61
	v_exp_f32_e32 v89, v68
	v_sub_f32_e32 v65, v65, v3
	v_mul_f32_e32 v69, 0x3fb8aa3b, v69
	v_exp_f32_e32 v88, v61
	v_sub_f32_e32 v72, v84, v3
	v_mul_f32_e32 v65, 0x3fb8aa3b, v65
	v_exp_f32_e32 v85, v69
	v_sub_f32_e32 v73, v73, v3
	v_sub_f32_e32 v81, v81, v3
	v_mul_f32_e32 v72, 0x3fb8aa3b, v72
	v_exp_f32_e32 v65, v65
	v_add_f32_e32 v68, 0, v97
	v_mul_f32_e32 v73, 0x3fb8aa3b, v73
	v_exp_f32_e32 v61, v72
	v_add_f32_e32 v68, v89, v68
	v_mul_f32_e32 v69, 0x3fb8aa3b, v81
	v_exp_f32_e32 v53, v73
	v_add_f32_e32 v68, v88, v68
	v_exp_f32_e32 v81, v69
	v_sub_f32_e32 v69, v77, v3
	v_add_f32_e32 v68, v85, v68
	v_mul_f32_e32 v69, 0x3fb8aa3b, v69
	v_add_f32_e32 v68, v65, v68
	v_exp_f32_e32 v84, v69
	v_add_f32_e32 v68, v61, v68
	v_add_f32_e32 v68, v53, v68
	v_add_f32_e32 v68, v81, v68
	v_add_f32_e32 v68, v84, v68
	s_nop 1
	v_mov_b32_dpp v69, v68 quad_perm:[1,0,3,2] row_mask:0xf bank_mask:0xf
	v_mov_b32_e32 v72, 0xf149f2ca
	v_lshl_add_u32 v77, v118, 2, s7
	v_mov_b32_e32 v73, 0xf149f2ca
	s_waitcnt lgkmcnt(0)
	v_add_f32_e32 v68, v68, v69
	s_nop 1
	v_mov_b32_dpp v69, v68 quad_perm:[2,3,0,1] row_mask:0xf bank_mask:0xf
	s_waitcnt lgkmcnt(0)
	v_add_f32_e32 v68, v68, v69
	s_nop 1
	v_mov_b32_dpp v69, v68 row_shl:4 row_mask:0xf bank_mask:0x5
	v_mov_b32_dpp v69, v68 row_shr:4 row_mask:0xf bank_mask:0xa
	s_waitcnt lgkmcnt(0)
	v_add_f32_e32 v68, v68, v69
	s_nop 1
	v_mov_b32_dpp v69, v68 row_shl:8 row_mask:0xf bank_mask:0x3
	v_mov_b32_dpp v69, v68 row_shr:8 row_mask:0xf bank_mask:0xc
	v_add_f32_e32 v203, v62, v203
	v_cndmask_b32_e64 v73, v73, v203, s[8:9]
	v_add_f32_e32 v204, v66, v204
	v_cndmask_b32_e64 v72, v72, v204, s[62:63]
	v_mov_b32_e32 v62, 0xf149f2ca
	v_mov_b32_e32 v66, 0xf149f2ca
	v_add_f32_e32 v205, v70, v205
	v_cndmask_b32_e64 v66, v66, v205, s[64:65]
	v_add_f32_e32 v206, v74, v206
	v_cndmask_b32_e64 v62, v62, v206, s[66:67]
	v_mov_b32_e32 v74, 0xf149f2ca
	v_mov_b32_e32 v178, 0xf149f2ca
	v_add_f32_e32 v207, v78, v207
	v_cndmask_b32_e64 v178, v178, v207, s[68:69]
	v_add_f32_e32 v208, v82, v208
	v_cndmask_b32_e64 v74, v74, v208, s[70:71]
	v_mov_b32_e32 v78, 0xf149f2ca
	v_mov_b32_e32 v82, 0xf149f2ca
	v_add_f32_e32 v209, v86, v209
	v_cndmask_b32_e64 v82, v82, v209, s[72:73]
	v_add_f32_e32 v210, v90, v210
	v_cndmask_b32_e64 v78, v78, v210, s[38:39]
	v_readlane_b32 s0, v255, 6
	v_readlane_b32 s1, v255, 7
	s_and_b64 s[0:1], s[0:1], s[76:77]
	s_and_b64 s[8:9], s[0:1], s[78:79]
	v_mov_b32_e32 v77, 0xf149f2ca
	v_mov_b32_e32 v180, 0xf149f2ca
	v_add_f32_e32 v211, v54, v211
	v_cndmask_b32_e64 v180, v180, v211, s[8:9]
	v_max_f32_e32 v54, v73, v73
	v_max_f32_e32 v54, 0xff61b1e6, v54
	v_max3_f32 v54, v54, v72, v66
	v_max3_f32 v54, v54, v62, v178
	v_max3_f32 v54, v54, v74, v82
	v_max3_f32 v54, v54, v78, v180
	s_nop 1
	v_mov_b32_dpp v70, v54 quad_perm:[1,0,3,2] row_mask:0xf bank_mask:0xf
	v_readlane_b32 s0, v255, 12
	v_readlane_b32 s1, v255, 13
	s_and_b64 s[0:1], s[0:1], vcc
	s_and_b64 s[8:9], s[0:1], s[74:75]
	s_waitcnt lgkmcnt(0)
	v_max_f32_e32 v70, v70, v70
	v_max_f32_e32 v54, v54, v70
	s_nop 1
	v_mov_b32_dpp v70, v54 quad_perm:[2,3,0,1] row_mask:0xf bank_mask:0xf
	s_waitcnt lgkmcnt(0)
	v_max_f32_e32 v70, v70, v70
	v_max_f32_e32 v54, v54, v70
	s_nop 1
	v_mov_b32_dpp v70, v54 row_shl:4 row_mask:0xf bank_mask:0x5
	v_mov_b32_dpp v70, v54 row_shr:4 row_mask:0xf bank_mask:0xa
	s_waitcnt lgkmcnt(0)
	v_max_f32_e32 v70, v70, v70
	v_max_f32_e32 v54, v54, v70
	s_nop 1
	v_mov_b32_dpp v70, v54 row_shl:8 row_mask:0xf bank_mask:0x3
	v_mov_b32_dpp v70, v54 row_shr:8 row_mask:0xf bank_mask:0xc
	s_waitcnt lgkmcnt(0)
	v_max_f32_e32 v70, v70, v70
	v_max_f32_e32 v70, v54, v70
	v_sub_f32_e32 v54, v73, v70
	v_sub_f32_e32 v72, v72, v70
	v_mul_f32_e32 v54, 0x3fb8aa3b, v54
	v_sub_f32_e32 v66, v66, v70
	v_mul_f32_e32 v72, 0x3fb8aa3b, v72
	v_exp_f32_e32 v179, v54
	v_sub_f32_e32 v62, v62, v70
	v_sub_f32_e32 v73, v178, v70
	v_mul_f32_e32 v66, 0x3fb8aa3b, v66
	v_exp_f32_e32 v178, v72
	v_mul_f32_e32 v62, 0x3fb8aa3b, v62
	v_exp_f32_e32 v90, v66
	v_sub_f32_e32 v74, v74, v70
	v_mul_f32_e32 v73, 0x3fb8aa3b, v73
	v_exp_f32_e32 v86, v62
	v_sub_f32_e32 v82, v82, v70
	v_sub_f32_e32 v78, v78, v70
	v_mul_f32_e32 v74, 0x3fb8aa3b, v74
	v_exp_f32_e32 v66, v73
	v_add_f32_e32 v72, 0, v179
	v_mul_f32_e32 v82, 0x3fb8aa3b, v82
	v_exp_f32_e32 v62, v74
	v_add_f32_e32 v72, v178, v72
	v_mul_f32_e32 v73, 0x3fb8aa3b, v78
	v_exp_f32_e32 v54, v82
	v_add_f32_e32 v72, v90, v72
	v_exp_f32_e32 v78, v73
	v_sub_f32_e32 v73, v180, v70
	v_add_f32_e32 v72, v86, v72
	v_mul_f32_e32 v73, 0x3fb8aa3b, v73
	v_add_f32_e32 v72, v66, v72
	v_exp_f32_e32 v82, v73
	v_add_f32_e32 v72, v62, v72
	v_add_f32_e32 v72, v54, v72
	v_add_f32_e32 v72, v78, v72
	v_add_f32_e32 v72, v82, v72
	s_nop 1
	v_mov_b32_dpp v73, v72 quad_perm:[1,0,3,2] row_mask:0xf bank_mask:0xf
	v_lshl_add_u32 v74, v120, 2, s7
	s_waitcnt lgkmcnt(0)
; __device__ __forceinline__ bf16_t f2bf(float f) { return (bf16_t)(cvt_pk_bf16(f, 0.f) & 0xffffu); }
; __device__ void attn_items(const Params& p, unsigned char* shm) {
;     ...
;         for (int i = 0; i < 4; ++i) { const int qi = fq * 4 + i; float m = -3.0e38f;
; #pragma unroll
;             for (int kt = 0; kt < 9; ++kt) { const int rel = 16 * kt + fr - 64 - qi, klat = G.q0 - 64 + 16 * w + 16 * kt + fr;
;                 const bool ok = rel >= -64 && rel <= 64 && klat >= 0 && klat < G.n_lat; const int bi = min(max(rel + 64, 0), 128);
;                 const float v = ok ? s[kt][i] + bs[bi] : -1.0e30f; s[kt][i] = v; m = fmaxf(m, v); }
;             m = fmaxf(m, __shfl_xor(m, 1)); m = fmaxf(m, __shfl_xor(m, 2)); m = fmaxf(m, __shfl_xor(m, 4)); m = fmaxf(m, __shfl_xor(m, 8));
;             float sum = 0.f;
; #pragma unroll
;             for (int kt = 0; kt < 9; ++kt) { const float pv = __expf(s[kt][i] - m); s[kt][i] = pv; sum += pv; }
;             sum += __shfl_xor(sum, 1); sum += __shfl_xor(sum, 2); sum += __shfl_xor(sum, 4); sum += __shfl_xor(sum, 8);
;             mx[i] = m; ls[i] = sum; }
;         bf16_t* Pw = Ps + w * 16 * 168;
; #pragma unroll
;         for (int i = 0; i < 4; ++i) {
; #pragma unroll
;             for (int kt = 0; kt < 9; ++kt) Pw[(fq * 4 + i) * 168 + 16 * kt + fr] = f2bf(s[kt][i]);
;             Pw[(fq * 4 + i) * 168 + 144 + fr] = 0; }
;         __syncthreads();
	v_add_f32_e32 v72, v72, v73
	s_nop 1
	v_mov_b32_dpp v73, v72 quad_perm:[2,3,0,1] row_mask:0xf bank_mask:0xf
	s_waitcnt lgkmcnt(0)
	v_add_f32_e32 v72, v72, v73
	s_nop 1
	v_mov_b32_dpp v73, v72 row_shl:4 row_mask:0xf bank_mask:0x5
	v_mov_b32_dpp v73, v72 row_shr:4 row_mask:0xf bank_mask:0xa
	s_waitcnt lgkmcnt(0)
	v_add_f32_e32 v72, v72, v73
	s_nop 1
	v_mov_b32_dpp v73, v72 row_shl:8 row_mask:0xf bank_mask:0x3
	v_mov_b32_dpp v73, v72 row_shr:8 row_mask:0xf bank_mask:0xc
	v_add_f32_e32 v212, v63, v212
	v_cndmask_b32_e64 v77, v77, v212, s[8:9]
	v_mov_b32_e32 v181, 0xf149f2ca
	v_mov_b32_e32 v183, 0xf149f2ca
	v_add_f32_e32 v213, v67, v213
	v_cndmask_b32_e64 v183, v183, v213, s[62:63]
	v_add_f32_e32 v214, v71, v214
	v_cndmask_b32_e64 v181, v181, v214, s[64:65]
	v_mov_b32_e32 v180, 0xf149f2ca
	v_mov_b32_e32 v182, 0xf149f2ca
	v_add_f32_e32 v215, v75, v215
	v_cndmask_b32_e64 v182, v182, v215, s[66:67]
	v_add_f32_e32 v216, v79, v216
	v_cndmask_b32_e64 v180, v180, v216, s[68:69]
	v_mov_b32_e32 v75, 0xf149f2ca
	v_mov_b32_e32 v79, 0xf149f2ca
	v_add_f32_e32 v217, v83, v217
	v_cndmask_b32_e64 v79, v79, v217, s[70:71]
	v_add_f32_e32 v218, v87, v218
	v_cndmask_b32_e64 v75, v75, v218, s[72:73]
	v_mov_b32_e32 v63, 0xf149f2ca
	v_mov_b32_e32 v67, 0xf149f2ca
	v_add_f32_e32 v219, v91, v219
	v_cndmask_b32_e64 v67, v67, v219, s[38:39]
	v_readlane_b32 s0, v255, 8
	v_readlane_b32 s1, v255, 9
	s_and_b64 s[0:1], s[0:1], s[76:77]
	s_and_b64 s[8:9], s[0:1], s[78:79]
	v_add_f32_e32 v220, v55, v220
	v_cndmask_b32_e64 v63, v63, v220, s[8:9]
	v_max_f32_e32 v55, v77, v77
	v_max_f32_e32 v55, 0xff61b1e6, v55
	v_max3_f32 v55, v55, v183, v181
	v_max3_f32 v55, v55, v182, v180
	v_max3_f32 v55, v55, v79, v75
	v_max3_f32 v55, v55, v67, v63
	s_nop 1
	v_mov_b32_dpp v71, v55 quad_perm:[1,0,3,2] row_mask:0xf bank_mask:0xf
	v_cvt_pk_bf16_f32 v52, v52, v1
	ds_write_b16 v172, v52 offset:192
	v_cvt_pk_bf16_f32 v52, v58, v1
	ds_write_b16 v172, v52 offset:224
	s_waitcnt lgkmcnt(2)
	v_max_f32_e32 v71, v71, v71
	v_max_f32_e32 v55, v55, v71
	s_nop 1
	v_mov_b32_dpp v71, v55 quad_perm:[2,3,0,1] row_mask:0xf bank_mask:0xf
	v_cvt_pk_bf16_f32 v52, v59, v1
	v_cvt_pk_bf16_f32 v80, v80, v1
	ds_write_b16 v172, v80
	v_cvt_pk_bf16_f32 v76, v76, v1
	s_waitcnt lgkmcnt(1)
	v_max_f32_e32 v71, v71, v71
	v_max_f32_e32 v55, v55, v71
	s_nop 1
	v_mov_b32_dpp v71, v55 row_shl:4 row_mask:0xf bank_mask:0x5
	v_mov_b32_dpp v71, v55 row_shr:4 row_mask:0xf bank_mask:0xa
	ds_write_b16 v172, v76 offset:32
	v_cvt_pk_bf16_f32 v64, v64, v1
	ds_write_b16 v172, v64 offset:64
	v_cvt_pk_bf16_f32 v60, v60, v1
	ds_write_b16 v172, v60 offset:96
	v_cvt_pk_bf16_f32 v57, v57, v1
	ds_write_b16 v172, v57 offset:128
	v_cvt_pk_bf16_f32 v56, v56, v1
	ds_write_b16 v172, v56 offset:160
	ds_write_b16 v172, v52 offset:256
	ds_write_b16 v122, v1 offset:288
	v_cvt_pk_bf16_f32 v52, v97, v1
	ds_write_b16 v175, v52
	v_cvt_pk_bf16_f32 v52, v89, v1
	ds_write_b16 v175, v52 offset:32
	v_cvt_pk_bf16_f32 v52, v88, v1
	ds_write_b16 v175, v52 offset:64
	v_cvt_pk_bf16_f32 v52, v85, v1
	s_waitcnt lgkmcnt(10)
	v_max_f32_e32 v71, v71, v71
	ds_write_b16 v175, v52 offset:96
	v_cvt_pk_bf16_f32 v52, v65, v1
	v_max_f32_e32 v55, v55, v71
	ds_write_b16 v175, v52 offset:128
	v_cvt_pk_bf16_f32 v52, v61, v1
	s_nop 1
	v_mov_b32_dpp v71, v55 row_shl:8 row_mask:0xf bank_mask:0x3
	v_mov_b32_dpp v71, v55 row_shr:8 row_mask:0xf bank_mask:0xc
	ds_write_b16 v175, v52 offset:160
	v_cvt_pk_bf16_f32 v52, v53, v1
	ds_write_b16 v175, v52 offset:192
	v_cvt_pk_bf16_f32 v52, v81, v1
	ds_write_b16 v175, v52 offset:224
	v_cvt_pk_bf16_f32 v52, v84, v1
	ds_write_b16 v175, v52 offset:256
	ds_write_b16 v123, v1 offset:288
	v_cvt_pk_bf16_f32 v52, v179, v1
	ds_write_b16 v175, v52 offset:336
	v_cvt_pk_bf16_f32 v52, v178, v1
	s_waitcnt lgkmcnt(6)
	v_max_f32_e32 v71, v71, v71
	ds_write_b16 v175, v52 offset:368
	v_cvt_pk_bf16_f32 v52, v90, v1
	v_max_f32_e32 v71, v55, v71
	ds_write_b16 v175, v52 offset:400
	v_cvt_pk_bf16_f32 v52, v86, v1
	v_sub_f32_e32 v55, v77, v71
	ds_write_b16 v175, v52 offset:432
	v_cvt_pk_bf16_f32 v52, v66, v1
	v_mul_f32_e32 v55, 0x3fb8aa3b, v55
	v_sub_f32_e32 v83, v183, v71
	ds_write_b16 v175, v52 offset:464
	v_cvt_pk_bf16_f32 v52, v62, v1
	v_exp_f32_e32 v55, v55
	v_mul_f32_e32 v83, 0x3fb8aa3b, v83
	v_sub_f32_e32 v87, v181, v71
	ds_write_b16 v175, v52 offset:496
	v_cvt_pk_bf16_f32 v52, v54, v1
	v_exp_f32_e32 v83, v83
	v_mul_f32_e32 v87, 0x3fb8aa3b, v87
	v_sub_f32_e32 v91, v182, v71
	ds_write_b16 v175, v52 offset:528
	v_cvt_pk_bf16_f32 v52, v78, v1
	v_add_f32_e32 v74, v176, v177
	v_exp_f32_e32 v87, v87
	v_mul_f32_e32 v91, 0x3fb8aa3b, v91
	v_sub_f32_e32 v176, v180, v71
	ds_write_b16 v175, v52 offset:560
	v_cvt_pk_bf16_f32 v52, v82, v1
	v_exp_f32_e32 v91, v91
	v_mul_f32_e32 v176, 0x3fb8aa3b, v176
	v_sub_f32_e32 v79, v79, v71
	ds_write_b16 v175, v52 offset:592
	ds_write_b16 v124, v1 offset:288
	v_cvt_pk_bf16_f32 v52, v55, v1
	v_add_f32_e32 v77, 0, v55
	v_exp_f32_e32 v176, v176
	v_mul_f32_e32 v79, 0x3fb8aa3b, v79
	v_sub_f32_e32 v75, v75, v71
	ds_write_b16 v175, v52 offset:672
	v_cvt_pk_bf16_f32 v52, v83, v1
	v_add_f32_e32 v77, v83, v77
	v_exp_f32_e32 v79, v79
	v_mul_f32_e32 v75, 0x3fb8aa3b, v75
	v_sub_f32_e32 v67, v67, v71
	ds_write_b16 v175, v52 offset:704
	v_cvt_pk_bf16_f32 v52, v87, v1
	v_add_f32_e32 v77, v87, v77
	v_exp_f32_e32 v177, v75
	v_mul_f32_e32 v67, 0x3fb8aa3b, v67
	v_sub_f32_e32 v63, v63, v71
	ds_write_b16 v175, v52 offset:736
	v_cvt_pk_bf16_f32 v52, v91, v1
	v_add_f32_e32 v77, v91, v77
	v_exp_f32_e32 v67, v67
	v_mul_f32_e32 v63, 0x3fb8aa3b, v63
	ds_write_b16 v175, v52 offset:768
	v_cvt_pk_bf16_f32 v52, v176, v1
	v_add_f32_e32 v77, v176, v77
	v_exp_f32_e32 v63, v63
	ds_write_b16 v175, v52 offset:800
	v_cvt_pk_bf16_f32 v52, v79, v1
	v_add_f32_e32 v77, v79, v77
	ds_write_b16 v175, v52 offset:832
	v_cvt_pk_bf16_f32 v52, v177, v1
	v_add_f32_e32 v75, v177, v77
	ds_write_b16 v175, v52 offset:864
	v_cvt_pk_bf16_f32 v52, v67, v1
	v_add_f32_e32 v75, v67, v75
	ds_write_b16 v175, v52 offset:896
	v_cvt_pk_bf16_f32 v52, v63, v1
	v_add_f32_e32 v75, v63, v75
	ds_write_b16 v175, v52 offset:928
	ds_write_b16 v125, v1 offset:288
	s_waitcnt lgkmcnt(0)
	s_barrier
; __device__ __forceinline__ bf16_t f2bf(float f) { return (bf16_t)(cvt_pk_bf16(f, 0.f) & 0xffffu); }
; __device__ void attn_items(const Params& p, unsigned char* shm) {
;     ...
;         f32x4 o[4];
; #pragma unroll
;         for (int nt = 0; nt < 4; ++nt) o[nt] = (f32x4){0.f, 0.f, 0.f, 0.f};
; #pragma unroll
;         for (int ks = 0; ks < 5; ++ks) { const bf16x8 ap = *(const bf16x8*)(Pw + fr * 168 + ks * 32 + fq * 8);
; #pragma unroll
;             for (int nt = 0; nt < 4; ++nt) { const int dim = nt * 16 + fr; o[nt] = __builtin_amdgcn_mfma_f32_16x16x32_bf16(ap, *(const bf16x8*)(Vt + dim * 320 + ((16 * w + ks * 32 + fq * 8) ^ ((dim >> 3) << 3))), o[nt], 0, 0, 0); } }
;         __syncthreads();
; #pragma unroll
;         for (int i = 0; i < 4; ++i) { const float inv = 1.0f / ls[i];
; #pragma unroll
;             for (int nt = 0; nt < 4; ++nt) Pw[(fq * 4 + i) * 168 + nt * 16 + fr] = f2bf(o[nt][i] * inv);
;             if (fr == 0) LSE[(size_t)(G.seq_start + G.r + G.dil * (G.q0 + 16 * w + fq * 4 + i)) * 24 + G.hd] = mx[i] + __logf(ls[i]); }
	ds_read_b128 v[52:55], v107
	ds_read_b128 v[56:59], v126 offset:36864
	ds_read_b128 v[60:63], v128 offset:36864
	ds_read_b128 v[64:67], v131 offset:36864
	ds_read_b128 v[78:81], v133 offset:36864
	s_waitcnt lgkmcnt(3)
	v_mfma_f32_16x16x32_bf16 v[56:59], v[52:55], v[56:59], 0
	s_mul_i32 s0, s58, 0xffffa000
	s_add_i32 s7, s2, s0
	s_and_b64 s[0:1], s[60:61], exec
	s_waitcnt lgkmcnt(2)
	v_mfma_f32_16x16x32_bf16 v[60:63], v[52:55], v[60:63], 0
	s_cselect_b32 s0, 4, 7
	s_sub_i32 s8, s0, s4
	s_and_b32 s7, s7, 0xfffff800
	s_waitcnt lgkmcnt(1)
	v_mfma_f32_16x16x32_bf16 v[64:67], v[52:55], v[64:67], 0
	s_and_b64 s[0:1], s[60:61], exec
	s_cselect_b32 s0, s7, 0x2000
	s_lshr_b32 s1, s6, s8
	s_waitcnt lgkmcnt(0)
	v_mfma_f32_16x16x32_bf16 v[52:55], v[52:55], v[78:81], 0
	ds_read_b128 v[78:81], v107 offset:64
	ds_read_b128 v[82:85], v134 offset:36864
	s_nop 1
	v_mov_b32_dpp v77, v75 quad_perm:[1,0,3,2] row_mask:0xf bank_mask:0xf
	s_ashr_i32 s59, s58, 31
	s_waitcnt lgkmcnt(0)
	v_mfma_f32_16x16x32_bf16 v[56:59], v[78:81], v[82:85], v[56:59]
	ds_read_b128 v[82:85], v135 offset:36864
	s_add_i32 s6, s1, s0
	s_lshl_b64 s[0:1], s[58:59], 2
	s_waitcnt lgkmcnt(0)
	v_mfma_f32_16x16x32_bf16 v[60:63], v[78:81], v[82:85], v[60:63]
	ds_read_b128 v[82:85], v136 offset:36864
	s_mov_b64 s[8:9], s[88:89]
	s_add_u32 s38, s8, s0
	s_waitcnt lgkmcnt(0)
	v_mfma_f32_16x16x32_bf16 v[64:67], v[78:81], v[82:85], v[64:67]
	ds_read_b128 v[82:85], v137 offset:36864
	s_addc_u32 s39, s9, s1
	v_add_f32_e32 v75, v75, v77
	s_waitcnt lgkmcnt(0)
	v_mfma_f32_16x16x32_bf16 v[52:55], v[78:81], v[82:85], v[52:55]
	ds_read_b128 v[78:81], v107 offset:128
	ds_read_b128 v[82:85], v138 offset:36864
	s_nop 1
	v_mov_b32_dpp v77, v75 quad_perm:[2,3,0,1] row_mask:0xf bank_mask:0xf
	v_add_u32_e32 v76, s5, v108
	s_waitcnt lgkmcnt(0)
	v_mfma_f32_16x16x32_bf16 v[56:59], v[78:81], v[82:85], v[56:59]
	ds_read_b128 v[82:85], v139 offset:36864
	s_waitcnt lgkmcnt(1)
	v_add_f32_e32 v75, v75, v77
	s_nop 1
	v_mov_b32_dpp v77, v75 row_shl:4 row_mask:0xf bank_mask:0x5
	v_mov_b32_dpp v77, v75 row_shr:4 row_mask:0xf bank_mask:0xa
	s_waitcnt lgkmcnt(0)
	v_mfma_f32_16x16x32_bf16 v[60:63], v[78:81], v[82:85], v[60:63]
	ds_read_b128 v[82:85], v140 offset:36864
	s_waitcnt lgkmcnt(1)
	v_add_f32_e32 v75, v75, v77
	s_nop 1
	v_mov_b32_dpp v77, v75 row_shl:8 row_mask:0xf bank_mask:0x3
	v_mov_b32_dpp v77, v75 row_shr:8 row_mask:0xf bank_mask:0xc
	s_waitcnt lgkmcnt(0)
	v_mfma_f32_16x16x32_bf16 v[64:67], v[78:81], v[82:85], v[64:67]
	ds_read_b128 v[82:85], v141 offset:36864
	s_waitcnt lgkmcnt(0)
	v_mfma_f32_16x16x32_bf16 v[78:81], v[78:81], v[82:85], v[52:55]
	ds_read_b128 v[82:85], v107 offset:192
	s_nop 1
	ds_read_b128 v[52:55], v142 offset:36864
	s_waitcnt lgkmcnt(0)
	v_mfma_f32_16x16x32_bf16 v[52:55], v[82:85], v[52:55], v[56:59]
	s_nop 2
	ds_read_b128 v[56:59], v143 offset:36864
	s_waitcnt lgkmcnt(0)
	v_mfma_f32_16x16x32_bf16 v[56:59], v[82:85], v[56:59], v[60:63]
	s_nop 2
	ds_read_b128 v[60:63], v144 offset:36864
	s_waitcnt lgkmcnt(0)
	v_mfma_f32_16x16x32_bf16 v[60:63], v[82:85], v[60:63], v[64:67]
	s_nop 2
	ds_read_b128 v[64:67], v145 offset:36864
	s_waitcnt lgkmcnt(0)
	v_mfma_f32_16x16x32_bf16 v[64:67], v[82:85], v[64:67], v[78:81]
	s_nop 2
	ds_read_b128 v[78:81], v107 offset:256
	ds_read_b128 v[82:85], v130 offset:36864
	s_waitcnt lgkmcnt(0)
	v_mfma_f32_16x16x32_bf16 v[52:55], v[78:81], v[82:85], v[52:55]
	ds_read_b128 v[82:85], v146 offset:36864
	s_waitcnt lgkmcnt(0)
	v_mfma_f32_16x16x32_bf16 v[56:59], v[78:81], v[82:85], v[56:59]
	ds_read_b128 v[82:85], v147 offset:36864
	s_waitcnt lgkmcnt(0)
	v_mfma_f32_16x16x32_bf16 v[60:63], v[78:81], v[82:85], v[60:63]
	ds_read_b128 v[82:85], v148 offset:36864
	s_waitcnt lgkmcnt(0)
	s_barrier
	v_mfma_f32_16x16x32_bf16 v[64:67], v[78:81], v[82:85], v[64:67]
	v_div_scale_f32 v78, s[0:1], v74, v74, 1.0
	v_rcp_f32_e32 v79, v78
	s_nop 0
	v_fma_f32 v80, -v78, v79, 1.0
	v_fmac_f32_e32 v79, v80, v79
	v_div_scale_f32 v80, vcc, 1.0, v74, 1.0
	v_mul_f32_e32 v81, v80, v79
	v_fma_f32 v82, -v78, v81, v80
	v_fmac_f32_e32 v81, v82, v79
	v_fma_f32 v78, -v78, v81, v80
	v_div_fmas_f32 v78, v78, v79, v81
	v_div_fixup_f32 v78, v78, v74, 1.0
	v_mul_f32_e32 v52, v78, v52
	v_cvt_pk_bf16_f32 v52, v52, v1
	ds_write_b16 v172, v52
	v_mul_f32_e32 v52, v78, v56
	v_cvt_pk_bf16_f32 v52, v52, v1
	ds_write_b16 v172, v52 offset:32
	v_mul_f32_e32 v52, v78, v60
	v_cvt_pk_bf16_f32 v52, v52, v1
	ds_write_b16 v172, v52 offset:64
	v_mul_f32_e32 v52, v78, v64
	v_cvt_pk_bf16_f32 v52, v52, v1
	ds_write_b16 v172, v52 offset:96
	s_and_saveexec_b64 s[0:1], s[36:37]
	s_cbranch_execz .LBB0_447
	s_mov_b32 s5, 0x800000
	v_cmp_gt_f32_e32 vcc, s5, v74
	s_mov_b32 s5, 0x3f317217
	v_mov_b64_e32 v[78:79], s[38:39]
	v_cndmask_b32_e64 v52, 0, 32, vcc
	v_ldexp_f32 v52, v74, v52
	v_log_f32_e32 v52, v52
	v_cndmask_b32_e32 v56, 0, v231, vcc
	v_mul_f32_e32 v60, 0x3f317217, v52
	v_fma_f32 v60, v52, s5, -v60
	v_fmac_f32_e32 v60, 0x3377d1cf, v52
	s_mov_b32 s5, 0x7f800000
	v_fmac_f32_e32 v60, 0x3f317217, v52
	v_cmp_lt_f32_e64 vcc, |v52|, s5
	s_nop 1
	v_cndmask_b32_e32 v52, v52, v60, vcc
	v_sub_f32_e32 v52, v52, v56
	v_add_f32_e32 v2, v2, v52
	v_lshlrev_b32_e32 v52, s4, v76
	v_add_u32_e32 v52, s6, v52
	v_mad_i64_i32 v[78:79], s[8:9], v52, s82, v[78:79]
	global_store_dword v[78:79], v2, off
